# attention: sliding 4-tile window (every wave starts on its own diagonal tile, 5-slot K/V ring) on top of the fused-chain VALU block
# baseline (speedup 1.0000x reference)
; #define LAS __attribute__((address_space(3)))
;     int tid_ = threadIdx.x; asm volatile("" : "+v"(tid_));
;     const int tid = tid_, lane = tid & 63, wid = __builtin_amdgcn_readfirstlane(tid >> 6), r32 = lane & 31, hi = lane >> 5;
;     const size_t rowbase = (size_t)b * SEQ;
;     const int q0 = qb * 256, qw = q0 + wid * 32;
;     bf16x8 qr[4];
;     { const bf16* qp = UGQ + (rowbase + qw + r32) * 2048 + 1024 + h * HD + hi * 8;
; #pragma unroll
;       for (int d0 = 0; d0 < 4; ++d0) qr[d0] = *(const bf16x8*)(qp + d0 * 16); }
;     f32x16 o0, o1;
; #pragma unroll
;     for (int r = 0; r < 16; ++r) { o0[r] = 0.f; o1[r] = 0.f; }
;     float C = 1.f; int alive = 1;
;     volatile LAS unsigned* aflag = (volatile LAS unsigned*)(lds + RING_BYTES);
;     const int NT = 4 * (qb + 1);
;     const int lkey = lane, lch = wid;
;     const int kk = lkey & 31, slot = (lkey & 32) | (8 * ((kk >> 2) & 3) + 4 * (kk >> 4) + (kk & 3));
;     const bf16* kg = Kb + (rowbase + lkey) * 1024 + h * HD + lch * 8;
;     const bf16* vg = Vb + (rowbase + lkey) * 1024 + h * HD + lch * 8;
;     u32x4 kreg, vreg;
;     kreg = *(const u32x4*)(kg + (size_t)(NT - 1) * 64 * 1024); vreg = *(const u32x4*)(vg + (size_t)(NT - 1) * 64 * 1024);
;     ...
;     AT_WRITE(0);
;     __syncthreads();
.LBB0_457:
	s_xor_b64 s[28:29], s[4:5], -1
	s_and_b64 s[4:5], s[4:5], exec
	v_readlane_b32 s1, v255, 48
	v_mov_b32_e32 v104, v232
	s_cselect_b32 s6, s1, s0
	v_readlane_b32 s12, v254, 58
	v_readfirstlane_b32 s1, v104
	s_ashr_i32 s33, s1, 6
	s_lshl_b32 s1, s6, 8
	s_lshl_b32 s24, s33, 5
	s_add_i32 s24, s24, s1
	s_ashr_i32 s4, s24, 31
	s_add_u32 s10, s18, s24
	v_and_b32_e32 v106, 31, v104
	s_addc_u32 s11, s19, s4
	v_or_b32_e32 v0, s10, v106
	v_mov_b32_e32 v1, s11
	v_bfe_u32 v4, v104, 5, 1
	v_lshlrev_b64 v[0:1], 12, v[0:1]
	v_lshl_add_u64 v[0:1], s[30:31], 0, v[0:1]
	v_lshlrev_b32_e32 v64, 4, v4
	v_lshl_add_u64 v[0:1], v[0:1], 0, v[64:65]
	global_load_dwordx4 v[66:69], v[0:1], off offset:2048
	global_load_dwordx4 v[70:73], v[0:1], off offset:2080
	global_load_dwordx4 v[74:77], v[0:1], off offset:2112
	global_load_dwordx4 v[78:81], v[0:1], off offset:2144
	v_lshlrev_b32_e32 v0, 1, v104
	v_lshrrev_b32_e32 v1, 2, v104
	v_and_b32_e32 v105, 63, v104
	v_and_b32_e32 v0, 24, v0
	v_and_b32_e32 v1, 4, v1
	v_and_b32_e32 v2, 35, v104
	v_or3_b32 v5, v2, v1, v0
	v_or_b32_e32 v0, s18, v105
	v_mov_b32_e32 v1, s19
	v_readlane_b32 s4, v255, 49
	v_lshlrev_b64 v[0:1], 11, v[0:1]
	v_readlane_b32 s5, v255, 50
	s_lshl_b32 s7, s6, 19
	v_readlane_b32 s13, v254, 59
	v_lshl_add_u64 v[2:3], s[4:5], 0, v[0:1]
	s_lshl_b32 s4, s33, 3
	s_ashr_i32 s5, s4, 31
	s_lshl_b64 s[4:5], s[4:5], 1
	v_lshl_add_u64 v[0:1], s[8:9], 0, v[0:1]
	v_lshl_add_u64 v[2:3], v[2:3], 0, s[4:5]
	v_lshl_add_u64 v[0:1], v[0:1], 0, s[4:5]
	s_mov_b32 s21, s13
	s_or_b32 s20, s7, 0x60000
	v_lshl_add_u64 v[2:3], v[2:3], 0, s[20:21]
	v_lshl_add_u64 v[0:1], v[0:1], 0, s[20:21]
	global_load_dwordx4 v[82:85], v[2:3], off
	global_load_dwordx4 v[86:89], v[0:1], off
	s_lshl_b32 s25, s6, 2
	s_lshl_b32 s6, s33, 10
	v_writelane_b32 v254, s12, 58
	s_add_i32 s20, s6, 0
	s_mul_i32 s6, s33, 0x480
	v_writelane_b32 v254, s13, 59
	s_add_i32 s6, s6, 0
	v_lshl_add_u32 v108, v105, 1, s6
	s_lshl_b32 s6, s33, 2
	v_readlane_b32 s12, v254, 57
	s_add_i32 s25, s25, 4
	s_add_i32 s26, s12, s6
	v_lshlrev_b32_e32 v0, 10, v4
	v_lshlrev_b32_e32 v1, 4, v106
	v_add3_u32 v111, 0, v0, v1
	v_mul_u32_u24_e32 v0, 0x90, v106
	v_and_b32_e32 v1, 32, v104
	s_add_u32 s4, s4, s7
	v_add3_u32 v112, 0, v0, v1
	v_lshlrev_b32_e32 v0, 11, v105
	v_mov_b32_e32 v1, v65
	s_addc_u32 s5, s5, 0
	v_lshl_add_u64 v[0:1], s[4:5], 0, v[0:1]
	v_mov_b32_e32 v14, v65
	v_mov_b32_e32 v15, v65
	v_lshl_add_u32 v107, v5, 4, s20
	v_lshl_add_u64 v[90:91], s[34:35], 0, v[0:1]
	v_lshl_add_u64 v[92:93], s[2:3], 0, v[0:1]
	global_load_dwordx4 v[156:159], v[90:91], off
	global_load_dwordx4 v[160:163], v[92:93], off
	v_lshl_add_u64 v[90:91], v[90:91], 0, s[16:17]
	v_lshl_add_u64 v[92:93], v[92:93], 0, s[16:17]
	global_load_dwordx4 v[168:171], v[90:91], off
	global_load_dwordx4 v[172:175], v[92:93], off
	v_lshl_add_u64 v[90:91], v[90:91], 0, s[16:17]
	v_lshl_add_u64 v[92:93], v[92:93], 0, s[16:17]
	global_load_dwordx4 v[176:179], v[90:91], off
	global_load_dwordx4 v[180:183], v[92:93], off
	v_lshl_add_u64 v[90:91], v[90:91], 0, s[16:17]
	v_lshl_add_u64 v[92:93], v[92:93], 0, s[16:17]
	v_add_u32_e32 v108, 0x6000, v108
	v_add_u32_e32 v112, 0x6000, v112
	v_add_u32_e32 v127, 0x2400, v108
	v_add_u32_e32 v128, 0x4800, v108
	v_add_u32_e32 v129, 0x6c00, v108
	v_mov_b32_e32 v0, v65
	v_mov_b32_e32 v1, v65
	v_mov_b32_e32 v2, v65
	v_mov_b32_e32 v3, v65
	v_mov_b32_e32 v4, v65
	v_mov_b32_e32 v5, v65
	v_mov_b32_e32 v6, v65
	v_mov_b32_e32 v7, v65
	v_mov_b32_e32 v8, v65
	v_mov_b32_e32 v9, v65
	v_mov_b32_e32 v10, v65
	v_mov_b32_e32 v11, v65
	v_mov_b32_e32 v12, v65
	v_mov_b32_e32 v13, v65
	v_mov_b64_e32 v[30:31], v[14:15]
	v_or_b32_e32 v109, s24, v106
	v_lshl_add_u32 v110, v105, 2, s12
	v_cmp_gt_u32_e64 s[36:37], 32, v105
	s_mov_b32 s6, 0
	v_cmp_eq_u32_e64 s[38:39], 0, v105
	v_cmp_gt_u32_e64 s[40:41], 8, v105
	s_lshr_b32 s99, s33, 1
	s_lshl_b32 s98, s99, 6
	s_add_i32 s27, s1, s98
	s_sub_i32 s99, 3, s99
	s_mov_b32 s100, 4
	v_mov_b32_e32 v95, 1.0
	v_mov_b32_e32 v32, 1
	v_mov_b64_e32 v[28:29], v[12:13]
	v_mov_b64_e32 v[26:27], v[10:11]
	v_mov_b64_e32 v[24:25], v[8:9]
	v_mov_b64_e32 v[22:23], v[6:7]
	v_mov_b64_e32 v[20:21], v[4:5]
	v_mov_b64_e32 v[18:19], v[2:3]
	v_mov_b64_e32 v[16:17], v[0:1]
	s_barrier
	s_waitcnt vmcnt(7)
	ds_write_b128 v107, v[82:85]
	s_waitcnt vmcnt(6)
	ds_write_b16 v108, v86 offset:16384
	ds_write_b16_d16_hi v108, v86 offset:16528
	ds_write_b16 v108, v87 offset:16672
	ds_write_b16_d16_hi v108, v87 offset:16816
	ds_write_b16 v108, v88 offset:16960
	ds_write_b16_d16_hi v108, v88 offset:17104
	ds_write_b16 v108, v89 offset:17248
	ds_write_b16_d16_hi v108, v89 offset:17392
	s_waitcnt vmcnt(5)
	ds_write_b128 v107, v[156:159] offset:8192
	s_waitcnt vmcnt(4)
	ds_write_b16 v127, v160 offset:16384
	ds_write_b16_d16_hi v127, v160 offset:16528
	ds_write_b16 v127, v161 offset:16672
	ds_write_b16_d16_hi v127, v161 offset:16816
	ds_write_b16 v127, v162 offset:16960
	ds_write_b16_d16_hi v127, v162 offset:17104
	ds_write_b16 v127, v163 offset:17248
	ds_write_b16_d16_hi v127, v163 offset:17392
	s_waitcnt vmcnt(3)
	ds_write_b128 v107, v[168:171] offset:16384
	s_waitcnt vmcnt(2)
	ds_write_b16 v128, v172 offset:16384
	ds_write_b16_d16_hi v128, v172 offset:16528
	ds_write_b16 v128, v173 offset:16672
	ds_write_b16_d16_hi v128, v173 offset:16816
	ds_write_b16 v128, v174 offset:16960
	ds_write_b16_d16_hi v128, v174 offset:17104
	ds_write_b16 v128, v175 offset:17248
	ds_write_b16_d16_hi v128, v175 offset:17392
	s_waitcnt vmcnt(1)
	ds_write_b128 v107, v[176:179] offset:24576
	s_waitcnt vmcnt(0)
	ds_write_b16 v129, v180 offset:16384
	ds_write_b16_d16_hi v129, v180 offset:16528
	ds_write_b16 v129, v181 offset:16672
	ds_write_b16_d16_hi v129, v181 offset:16816
	ds_write_b16 v129, v182 offset:16960
	ds_write_b16_d16_hi v129, v182 offset:17104
	ds_write_b16 v129, v183 offset:17248
	ds_write_b16_d16_hi v129, v183 offset:17392
	s_waitcnt lgkmcnt(0)
	s_barrier
	s_cmp_eq_u32 s25, 0
	s_cbranch_scc0 .LBB0_459

; #define LAS __attribute__((address_space(3)))
;     ...
;     for (int it = 0; it < NT; ++it) {
;         const int kt = NT - 1 - it, cur = it & 1;
;         if (it + 1 < NT) { kreg = *(const u32x4*)(kg + (size_t)(kt - 1) * 64 * 1024); vreg = *(const u32x4*)(vg + (size_t)(kt - 1) * 64 * 1024); }
;         const int k0 = kt * 64;
;         if (k0 < qw + 32 && alive) {
;             const LAS unsigned char* kb = lds + AT_K + cur * 8192 + hi * 1024 + r32 * 16;
;             f32x16 p0, p1;
; #pragma unroll
;             for (int r = 0; r < 16; ++r) { p0[r] = 0.f; p1[r] = 0.f; }
; #pragma unroll
;             for (int d0 = 0; d0 < 4; ++d0) {
;                 const bf16x8 a0 = *(const LAS bf16x8*)(kb + d0 * 2048), a1 = *(const LAS bf16x8*)(kb + d0 * 2048 + 512);
;                 p0 = __builtin_amdgcn_mfma_f32_32x32x16_bf16(a0, qr[d0], p0, 0, 0, 0);
;                 p1 = __builtin_amdgcn_mfma_f32_32x32x16_bf16(a1, qr[d0], p1, 0, 0, 0);
;             }
; #pragma unroll
;             for (int r = 0; r < 16; ++r) { p0[r] = __builtin_amdgcn_rcpf(1.f + __builtin_amdgcn_exp2f(p0[r])); p1[r] = __builtin_amdgcn_rcpf(1.f + __builtin_amdgcn_exp2f(p1[r])); }
;             if (k0 + 63 >= qw) {
;                 const int kb0 = k0 + 16 * hi;
; #pragma unroll
;                 for (int r = 0; r < 16; ++r) { if (kb0 + r >= qrel) p0[r] = 1.f; if (kb0 + 32 + r >= qrel) p1[r] = 1.f; }
;             }
.LBB0_459:
	s_add_i32 s21, s6, 1
	s_add_i32 s98, s6, 4
	s_cmp_lt_u32 s98, s25
	s_cselect_b64 s[12:13], -1, 0
	s_cmp_ge_u32 s98, s25
	s_cbranch_scc1 .LBB0_461
	global_load_dwordx4 v[82:85], v[90:91], off
	global_load_dwordx4 v[86:89], v[92:93], off
.LBB0_461:
	s_and_b32 s1, s6, 1
	s_cmp_ge_i32 s27, 0
	s_cselect_b64 s[4:5], -1, 0
	v_cmp_ne_u32_e32 vcc, 0, v32
	s_and_b64 s[4:5], s[4:5], vcc
	s_andn2_b64 vcc, exec, s[4:5]
	s_cbranch_vccnz .LBB0_471
	v_lshl_add_u32 v94, s99, 13, v111
	s_mul_i32 s98, s99, 0x2400
	ds_read_b128 v[156:159], v94
	ds_read_b128 v[160:163], v94 offset:2048
	ds_read_b128 v[168:171], v94 offset:4096
	ds_read_b128 v[172:175], v94 offset:6144
	ds_read_b128 v[176:179], v94 offset:512
	ds_read_b128 v[180:183], v94 offset:2560
	ds_read_b128 v[184:187], v94 offset:4608
	ds_read_b128 v[188:191], v94 offset:6656
	v_add_u32_e32 v126, s98, v112
	s_add_i32 s4, s27, 63
	s_cmp_lt_i32 s4, s24
	s_waitcnt lgkmcnt(7)
	v_mfma_f32_32x32x16_bf16 v[32:47], v[156:159], v[66:69], 0
	ds_read_b128 v[206:209], v126 offset:16384
	s_waitcnt lgkmcnt(7)
	v_mfma_f32_32x32x16_bf16 v[32:47], v[160:163], v[70:73], v[32:47]
	ds_read_b128 v[210:213], v126 offset:20992
	s_waitcnt lgkmcnt(7)
	v_mfma_f32_32x32x16_bf16 v[32:47], v[168:171], v[74:77], v[32:47]
	ds_read_b128 v[214:217], v126 offset:16400
	s_waitcnt lgkmcnt(7)
	v_mfma_f32_32x32x16_bf16 v[32:47], v[172:175], v[78:81], v[32:47]
	ds_read_b128 v[218:221], v126 offset:21008
	s_waitcnt lgkmcnt(7)
	v_mfma_f32_32x32x16_bf16 v[48:63], v[176:179], v[66:69], 0
	ds_read_b128 v[222:225], v126 offset:16448
	s_waitcnt lgkmcnt(7)
	v_mfma_f32_32x32x16_bf16 v[48:63], v[180:183], v[70:73], v[48:63]
	ds_read_b128 v[226:229], v126 offset:21056
	s_waitcnt lgkmcnt(7)
	v_mfma_f32_32x32x16_bf16 v[48:63], v[184:187], v[74:77], v[48:63]
	ds_read_b128 v[118:121], v126 offset:16464
	s_waitcnt lgkmcnt(7)
	v_mfma_f32_32x32x16_bf16 v[48:63], v[188:191], v[78:81], v[48:63]
	ds_read_b128 v[122:125], v126 offset:21072
	v_exp_f32_e32 v32, v32
	v_exp_f32_e32 v33, v33
	v_exp_f32_e32 v34, v34
	v_exp_f32_e32 v35, v35
	v_exp_f32_e32 v36, v36
	v_exp_f32_e32 v37, v37
	v_exp_f32_e32 v38, v38
	v_exp_f32_e32 v39, v39
	v_exp_f32_e32 v40, v40
	v_exp_f32_e32 v41, v41
	v_exp_f32_e32 v42, v42
	v_exp_f32_e32 v43, v43
	v_exp_f32_e32 v44, v44
	v_exp_f32_e32 v45, v45
	v_exp_f32_e32 v46, v46
	v_exp_f32_e32 v47, v47
	v_exp_f32_e32 v48, v48
	v_exp_f32_e32 v49, v49
	v_exp_f32_e32 v50, v50
	v_exp_f32_e32 v51, v51
	v_exp_f32_e32 v52, v52
	v_exp_f32_e32 v53, v53
	v_exp_f32_e32 v54, v54
	v_exp_f32_e32 v55, v55
	v_exp_f32_e32 v56, v56
	v_exp_f32_e32 v57, v57
	v_exp_f32_e32 v58, v58
	v_exp_f32_e32 v59, v59
	v_exp_f32_e32 v60, v60
	v_exp_f32_e32 v61, v61
	v_exp_f32_e32 v62, v62
	v_exp_f32_e32 v63, v63
	s_cbranch_scc1 .Lattn_nomask
	v_sub_u32_e32 v230, v109, v64
	v_subrev_u32_e32 v230, s27, v230
	v_cmp_gt_i32_e64 s[42:43], v230, 0
	v_cmp_gt_i32_e64 s[44:45], v230, 1
	v_cmp_gt_i32_e64 s[46:47], v230, 2
	v_cmp_gt_i32_e64 s[48:49], v230, 3
	v_cndmask_b32_e64 v32, 0, v32, s[42:43]
	v_cndmask_b32_e64 v33, 0, v33, s[44:45]
	v_cndmask_b32_e64 v34, 0, v34, s[46:47]
	v_cndmask_b32_e64 v35, 0, v35, s[48:49]
	v_cmp_gt_i32_e64 s[42:43], v230, 4
	v_cmp_gt_i32_e64 s[44:45], v230, 5
	v_cmp_gt_i32_e64 s[46:47], v230, 6
	v_cmp_gt_i32_e64 s[48:49], v230, 7
	v_cndmask_b32_e64 v36, 0, v36, s[42:43]
	v_cndmask_b32_e64 v37, 0, v37, s[44:45]
	v_cndmask_b32_e64 v38, 0, v38, s[46:47]
	v_cndmask_b32_e64 v39, 0, v39, s[48:49]
	v_cmp_gt_i32_e64 s[42:43], v230, 8
	v_cmp_gt_i32_e64 s[44:45], v230, 9
	v_cmp_gt_i32_e64 s[46:47], v230, 10
	v_cmp_gt_i32_e64 s[48:49], v230, 11
	v_cndmask_b32_e64 v40, 0, v40, s[42:43]
	v_cndmask_b32_e64 v41, 0, v41, s[44:45]
	v_cndmask_b32_e64 v42, 0, v42, s[46:47]
	v_cndmask_b32_e64 v43, 0, v43, s[48:49]
	v_cmp_gt_i32_e64 s[42:43], v230, 12
	v_cmp_gt_i32_e64 s[44:45], v230, 13
	v_cmp_gt_i32_e64 s[46:47], v230, 14
	v_cmp_gt_i32_e64 s[48:49], v230, 15
	v_cndmask_b32_e64 v44, 0, v44, s[42:43]
	v_cndmask_b32_e64 v45, 0, v45, s[44:45]
	v_cndmask_b32_e64 v46, 0, v46, s[46:47]
	v_cndmask_b32_e64 v47, 0, v47, s[48:49]
	v_cmp_gt_i32_e64 s[42:43], v230, 32
	v_cmp_gt_i32_e64 s[44:45], v230, 33
	v_cmp_gt_i32_e64 s[46:47], v230, 34
	v_cmp_gt_i32_e64 s[48:49], v230, 35
	v_cndmask_b32_e64 v48, 0, v48, s[42:43]
	v_cndmask_b32_e64 v49, 0, v49, s[44:45]
	v_cndmask_b32_e64 v50, 0, v50, s[46:47]
	v_cndmask_b32_e64 v51, 0, v51, s[48:49]
	v_cmp_gt_i32_e64 s[42:43], v230, 36
	v_cmp_gt_i32_e64 s[44:45], v230, 37
	v_cmp_gt_i32_e64 s[46:47], v230, 38
	v_cmp_gt_i32_e64 s[48:49], v230, 39
	v_cndmask_b32_e64 v52, 0, v52, s[42:43]
	v_cndmask_b32_e64 v53, 0, v53, s[44:45]
	v_cndmask_b32_e64 v54, 0, v54, s[46:47]
	v_cndmask_b32_e64 v55, 0, v55, s[48:49]
	v_cmp_gt_i32_e64 s[42:43], v230, 40
	v_cmp_gt_i32_e64 s[44:45], v230, 41
	v_cmp_gt_i32_e64 s[46:47], v230, 42
	v_cmp_gt_i32_e64 s[48:49], v230, 43
	v_cndmask_b32_e64 v56, 0, v56, s[42:43]
	v_cndmask_b32_e64 v57, 0, v57, s[44:45]
	v_cndmask_b32_e64 v58, 0, v58, s[46:47]
	v_cndmask_b32_e64 v59, 0, v59, s[48:49]
	v_cmp_gt_i32_e64 s[42:43], v230, 44
	v_cmp_gt_i32_e64 s[44:45], v230, 45
	v_cmp_gt_i32_e64 s[46:47], v230, 46
	v_cmp_gt_i32_e64 s[48:49], v230, 47
	v_cndmask_b32_e64 v60, 0, v60, s[42:43]
	v_cndmask_b32_e64 v61, 0, v61, s[44:45]
	v_cndmask_b32_e64 v62, 0, v62, s[46:47]
	v_cndmask_b32_e64 v63, 0, v63, s[48:49]

;     ...
;             alive = __any(C != 0.f);
;         }
;         if (it + 1 < NT) AT_WRITE(cur ^ 1);
;         if (lane == 0) aflag[(it & 1) * 8 + wid] = (unsigned)alive;
;         __syncthreads();
;         const unsigned fl = (lane < 8) ? aflag[(it & 1) * 8 + lane] : 0u;
;         if (!__any(fl != 0u)) break;
;     }
.LBB0_469:
	s_or_b64 exec, exec, s[4:5]
	v_cndmask_b32_e64 v33, 0, 1, s[6:7]
	v_cmp_ne_u32_e32 vcc, 0, v33
	s_cmp_eq_u64 vcc, 0
	s_cselect_b64 s[4:5], -1, 0
	v_lshl_add_u64 v[90:91], v[90:91], 0, s[16:17]
	v_lshl_add_u64 v[92:93], v[92:93], 0, s[16:17]
	s_sub_i32 s27, s27, 64
	s_add_i32 s99, s99, 1
	s_cmp_eq_u32 s99, 5
	s_cselect_b32 s99, 0, s99
	s_add_i32 s100, s100, 1
	s_cmp_eq_u32 s100, 5
	s_cselect_b32 s100, 0, s100
	s_and_b64 vcc, exec, s[4:5]
	s_cbranch_vccnz .LBB0_456
.LBB0_470:
	s_mov_b32 s6, s21
	s_cmp_ge_u32 s21, s25
	s_cbranch_scc1 .LBB0_458
	s_branch .LBB0_459
.LBB0_471:
	s_cmp_ge_i32 s27, 0
	s_cbranch_scc1 .Lattn_tile_ok
	v_mov_b32_e32 v32, 0

;     ...
;         if (it + 1 < NT) AT_WRITE(cur ^ 1);
.LBB0_472:
	s_mov_b32 s4, s100
	v_lshl_add_u32 v33, s4, 13, v107
	s_mulk_i32 s4, 0x2400
	s_waitcnt vmcnt(1)
	ds_write_b128 v33, v[82:85]
	v_add_u32_e32 v33, s4, v108
	s_waitcnt vmcnt(0)
	ds_write_b16 v33, v86 offset:16384
	ds_write_b16_d16_hi v33, v86 offset:16528
	ds_write_b16 v33, v87 offset:16672
	ds_write_b16_d16_hi v33, v87 offset:16816
	ds_write_b16 v33, v88 offset:16960
	ds_write_b16_d16_hi v33, v88 offset:17104
	ds_write_b16 v33, v89 offset:17248
	ds_write_b16_d16_hi v33, v89 offset:17392
	s_and_saveexec_b64 s[4:5], s[38:39]
	s_cbranch_execnz .LBB0_466
	s_branch .LBB0_467

; __global__ void __launch_bounds__(512, 2) fwd_kernel(Args a) {
	.amdhsa_kernel _Z10fwd_kernel4Args
		.amdhsa_group_segment_fixed_size 0
		.amdhsa_private_segment_fixed_size 0
		.amdhsa_kernarg_size 384
		.amdhsa_user_sgpr_count 2
		.amdhsa_user_sgpr_dispatch_ptr 0
		.amdhsa_user_sgpr_queue_ptr 0
		.amdhsa_user_sgpr_kernarg_segment_ptr 1
		.amdhsa_user_sgpr_dispatch_id 0
		.amdhsa_user_sgpr_kernarg_preload_length 0
		.amdhsa_user_sgpr_kernarg_preload_offset 0
		.amdhsa_user_sgpr_private_segment_size 0
		.amdhsa_uses_dynamic_stack 0
		.amdhsa_enable_private_segment 0
		.amdhsa_system_sgpr_workgroup_id_x 1
		.amdhsa_system_sgpr_workgroup_id_y 0
		.amdhsa_system_sgpr_workgroup_id_z 0
		.amdhsa_system_sgpr_workgroup_info 0
		.amdhsa_system_vgpr_workitem_id 2
		.amdhsa_next_free_vgpr 256
		.amdhsa_next_free_sgpr 102
		.amdhsa_accum_offset 256
		.amdhsa_reserve_vcc 1
		.amdhsa_float_round_mode_32 0
		.amdhsa_float_round_mode_16_64 0
		.amdhsa_float_denorm_mode_32 3
		.amdhsa_float_denorm_mode_16_64 3
		.amdhsa_dx10_clamp 1
		.amdhsa_ieee_mode 1
		.amdhsa_fp16_overflow 0
		.amdhsa_tg_split 0
		.amdhsa_exception_fp_ieee_invalid_op 0
		.amdhsa_exception_fp_denorm_src 0
		.amdhsa_exception_fp_ieee_div_zero 0
		.amdhsa_exception_fp_ieee_overflow 0
		.amdhsa_exception_fp_ieee_underflow 0
		.amdhsa_exception_fp_ieee_inexact 0
		.amdhsa_exception_int_div_zero 0
	.end_amdhsa_kernel

; __global__ void __launch_bounds__(512, 2) fwd_kernel(Args a) {
amdhsa.kernels:
  - .agpr_count:     0
    .args:
      - .offset:         0
        .size:           128
        .value_kind:     by_value
      - .offset:         128
        .size:           4
        .value_kind:     hidden_block_count_x
      - .offset:         132
        .size:           4
        .value_kind:     hidden_block_count_y
      - .offset:         136
        .size:           4
        .value_kind:     hidden_block_count_z
      - .offset:         140
        .size:           2
        .value_kind:     hidden_group_size_x
      - .offset:         142
        .size:           2
        .value_kind:     hidden_group_size_y
      - .offset:         144
        .size:           2
        .value_kind:     hidden_group_size_z
      - .offset:         146
        .size:           2
        .value_kind:     hidden_remainder_x
      - .offset:         148
        .size:           2
        .value_kind:     hidden_remainder_y
      - .offset:         150
        .size:           2
        .value_kind:     hidden_remainder_z
      - .offset:         168
        .size:           8
        .value_kind:     hidden_global_offset_x
      - .offset:         176
        .size:           8
        .value_kind:     hidden_global_offset_y
      - .offset:         184
        .size:           8
        .value_kind:     hidden_global_offset_z
      - .offset:         192
        .size:           2
        .value_kind:     hidden_grid_dims
      - .offset:         216
        .size:           8
        .value_kind:     hidden_multigrid_sync_arg
      - .offset:         248
        .size:           4
        .value_kind:     hidden_dynamic_lds_size
    .group_segment_fixed_size: 0
    .kernarg_segment_align: 8
    .kernarg_segment_size: 384
    .language:       OpenCL C
    .language_version:
      - 2
      - 0
    .max_flat_workgroup_size: 512
    .name:           _Z10fwd_kernel4Args
    .private_segment_fixed_size: 0
    .sgpr_count:     108
    .sgpr_spill_count: 269
    .symbol:         _Z10fwd_kernel4Args.kd
    .uniform_work_group_size: 1
    .uses_dynamic_stack: false
    .vgpr_count:     256
    .vgpr_spill_count: 0
    .wavefront_size: 64
